# chunk-state phase: second-half xsT loads issued at top of each inner iteration (two dests renamed) so their latency overlaps first-half work
# speedup vs baseline: 1.0162x; 1.0008x over previous
.LBB0_694:
	v_lshl_add_u64 v[138:139], v[200:201], 0, s[18:19]
	v_add_co_u32_e32 v208, vcc, s26, v138
	v_add_co_u32_e64 v206, s[0:1], s27, v138
	v_add_co_u32_e64 v204, s[2:3], s28, v138
	v_add_co_u32_e64 v202, s[4:5], s29, v138
	v_addc_co_u32_e32 v209, vcc, 0, v139, vcc
	ds_read_b128 v[134:137], v199
	ds_read_b128 v[130:133], v199 offset:16
	ds_read_b128 v[146:149], v216
	v_addc_co_u32_e64 v207, vcc, 0, v139, s[0:1]
	v_addc_co_u32_e64 v205, vcc, 0, v139, s[2:3]
	v_addc_co_u32_e64 v203, vcc, 0, v139, s[4:5]
	global_load_dwordx4 v[138:141], v[208:209], off
	global_load_dwordx4 v[142:145], v[206:207], off
	global_load_dwordx4 v[150:153], v[204:205], off
	global_load_dwordx4 v[154:157], v[202:203], off
	global_load_dwordx4 v[222:225], v[208:209], off offset:64
	global_load_dwordx4 v[226:229], v[202:203], off offset:64
	global_load_dwordx4 v[232:235], v[206:207], off offset:64
	global_load_dwordx4 v[236:239], v[204:205], off offset:64
	s_add_u32 s18, s18, 0x80
	s_addc_u32 s19, s19, 0
	s_cmpk_lg_i32 s18, 0x100
	s_waitcnt vmcnt(7)
	v_lshlrev_b32_e32 v158, 16, v138
	v_and_b32_e32 v159, 0xffff0000, v138
	v_lshlrev_b32_e32 v138, 16, v139
	v_and_b32_e32 v139, 0xffff0000, v139
	v_lshlrev_b32_e32 v160, 16, v140
	v_and_b32_e32 v161, 0xffff0000, v140
	v_lshlrev_b32_e32 v140, 16, v141
	v_and_b32_e32 v141, 0xffff0000, v141
	s_waitcnt vmcnt(6)
	v_lshlrev_b32_e32 v162, 16, v142
	v_and_b32_e32 v163, 0xffff0000, v142
	v_lshlrev_b32_e32 v142, 16, v143
	v_and_b32_e32 v143, 0xffff0000, v143
	v_lshlrev_b32_e32 v164, 16, v144
	v_and_b32_e32 v165, 0xffff0000, v144
	v_lshlrev_b32_e32 v144, 16, v145
	v_and_b32_e32 v145, 0xffff0000, v145
	s_waitcnt vmcnt(5)
	v_lshlrev_b32_e32 v166, 16, v150
	v_and_b32_e32 v167, 0xffff0000, v150
	v_lshlrev_b32_e32 v150, 16, v151
	v_and_b32_e32 v151, 0xffff0000, v151
	v_lshlrev_b32_e32 v168, 16, v152
	v_and_b32_e32 v169, 0xffff0000, v152
	v_lshlrev_b32_e32 v152, 16, v153
	v_and_b32_e32 v153, 0xffff0000, v153
	s_waitcnt vmcnt(4)
	v_lshlrev_b32_e32 v170, 16, v154
	v_and_b32_e32 v171, 0xffff0000, v154
	v_lshlrev_b32_e32 v154, 16, v155
	v_and_b32_e32 v155, 0xffff0000, v155
	v_lshlrev_b32_e32 v172, 16, v156
	v_and_b32_e32 v173, 0xffff0000, v156
	v_lshlrev_b32_e32 v156, 16, v157
	v_and_b32_e32 v157, 0xffff0000, v157
	s_waitcnt lgkmcnt(2)
	v_pk_mul_f32 v[158:159], v[134:135], v[158:159]
	v_pk_mul_f32 v[138:139], v[136:137], v[138:139]
	s_waitcnt lgkmcnt(1)
	v_pk_mul_f32 v[160:161], v[130:131], v[160:161]
	v_pk_mul_f32 v[140:141], v[132:133], v[140:141]
	v_pk_mul_f32 v[162:163], v[134:135], v[162:163]
	v_pk_mul_f32 v[142:143], v[136:137], v[142:143]
	v_pk_mul_f32 v[164:165], v[130:131], v[164:165]
	v_pk_mul_f32 v[144:145], v[132:133], v[144:145]
	v_pk_mul_f32 v[166:167], v[134:135], v[166:167]
	v_pk_mul_f32 v[150:151], v[136:137], v[150:151]
	v_pk_mul_f32 v[168:169], v[130:131], v[168:169]
	v_pk_mul_f32 v[152:153], v[132:133], v[152:153]
	v_pk_mul_f32 v[170:171], v[134:135], v[170:171]
	v_pk_mul_f32 v[154:155], v[136:137], v[154:155]
	v_pk_mul_f32 v[172:173], v[130:131], v[172:173]
	v_pk_mul_f32 v[156:157], v[132:133], v[156:157]
	v_cvt_pk_bf16_f32 v134, v158, v159
	v_cvt_pk_bf16_f32 v135, v138, v139
	v_cvt_pk_bf16_f32 v136, v160, v161
	v_cvt_pk_bf16_f32 v137, v140, v141
	v_cvt_pk_bf16_f32 v130, v162, v163
	v_cvt_pk_bf16_f32 v131, v142, v143
	v_cvt_pk_bf16_f32 v132, v164, v165
	v_cvt_pk_bf16_f32 v133, v144, v145
	v_cvt_pk_bf16_f32 v138, v166, v167
	v_cvt_pk_bf16_f32 v139, v150, v151
	v_cvt_pk_bf16_f32 v140, v168, v169
	v_cvt_pk_bf16_f32 v141, v152, v153
	v_cvt_pk_bf16_f32 v142, v170, v171
	v_cvt_pk_bf16_f32 v143, v154, v155
	v_cvt_pk_bf16_f32 v144, v172, v173
	v_cvt_pk_bf16_f32 v145, v156, v157
	s_waitcnt lgkmcnt(0)
	v_mfma_f32_16x16x32_bf16 v[98:101], v[146:149], v[134:137], v[98:101]
	v_mfma_f32_16x16x32_bf16 v[94:97], v[146:149], v[130:133], v[94:97]
	v_mfma_f32_16x16x32_bf16 v[82:85], v[146:149], v[138:141], v[82:85]
	v_mfma_f32_16x16x32_bf16 v[74:77], v[146:149], v[142:145], v[74:77]
	ds_read_b128 v[146:149], v216 offset:4352
	ds_read_b128 v[174:177], v216 offset:8704
	ds_read_b128 v[170:173], v216 offset:13056
	ds_read_b128 v[166:169], v216 offset:17408
	s_waitcnt lgkmcnt(3)
	v_mfma_f32_16x16x32_bf16 v[126:129], v[146:149], v[134:137], v[126:129]
	v_mfma_f32_16x16x32_bf16 v[122:125], v[146:149], v[130:133], v[122:125]
	v_mfma_f32_16x16x32_bf16 v[118:121], v[146:149], v[138:141], v[118:121]
	v_mfma_f32_16x16x32_bf16 v[110:113], v[146:149], v[142:145], v[110:113]
	ds_read_b128 v[162:165], v216 offset:21760
	ds_read_b128 v[158:161], v216 offset:26112
	ds_read_b128 v[146:149], v216 offset:30464
	ds_read_b128 v[154:157], v199 offset:128
	ds_read_b128 v[150:153], v199 offset:144
	ds_read_b128 v[218:221], v216 offset:64
	s_waitcnt lgkmcnt(8)
	v_mfma_f32_16x16x32_bf16 v[114:117], v[174:177], v[134:137], v[114:117]
	v_add_u32_e32 v199, 0x100, v199
	s_waitcnt vmcnt(2)
	v_lshlrev_b32_e32 v230, 16, v226
	v_mfma_f32_16x16x32_bf16 v[106:109], v[174:177], v[130:133], v[106:109]
	v_and_b32_e32 v231, 0xffff0000, v226
	v_lshlrev_b32_e32 v226, 16, v227
	v_and_b32_e32 v227, 0xffff0000, v227
	v_mfma_f32_16x16x32_bf16 v[70:73], v[174:177], v[138:141], v[70:73]
	v_mfma_f32_16x16x32_bf16 v[58:61], v[174:177], v[142:145], v[58:61]
	v_lshlrev_b32_e32 v202, 16, v222
	s_waitcnt lgkmcnt(3)
	v_mfma_f32_16x16x32_bf16 v[90:93], v[146:149], v[134:137], v[90:93]
	v_and_b32_e32 v203, 0xffff0000, v222
	v_lshlrev_b32_e32 v208, 16, v223
	v_and_b32_e32 v209, 0xffff0000, v223
	v_mfma_f32_16x16x32_bf16 v[86:89], v[146:149], v[130:133], v[86:89]
	s_waitcnt lgkmcnt(2)
	v_pk_mul_f32 v[202:203], v[154:155], v[202:203]
	v_pk_mul_f32 v[208:209], v[156:157], v[208:209]
	s_waitcnt vmcnt(1)
	v_lshlrev_b32_e32 v222, 16, v232
	v_mfma_f32_16x16x32_bf16 v[78:81], v[146:149], v[138:141], v[78:81]
	v_and_b32_e32 v223, 0xffff0000, v232
	v_lshlrev_b32_e32 v174, 16, v233
	v_and_b32_e32 v175, 0xffff0000, v233
	v_mfma_f32_16x16x32_bf16 v[102:105], v[146:149], v[142:145], v[102:105]
	ds_read_b128 v[146:149], v216 offset:4416
	v_pk_mul_f32 v[222:223], v[154:155], v[222:223]
	v_pk_mul_f32 v[174:175], v[156:157], v[174:175]
	v_mfma_f32_16x16x32_bf16 v[66:69], v[170:173], v[134:137], v[66:69]
	v_mfma_f32_16x16x32_bf16 v[62:65], v[170:173], v[130:133], v[62:65]
	v_mfma_f32_16x16x32_bf16 v[54:57], v[170:173], v[138:141], v[54:57]
	v_mfma_f32_16x16x32_bf16 v[50:53], v[170:173], v[142:145], v[50:53]
	v_lshlrev_b32_e32 v170, 16, v224
	v_and_b32_e32 v171, 0xffff0000, v224
	v_lshlrev_b32_e32 v172, 16, v225
	v_mfma_f32_16x16x32_bf16 v[46:49], v[166:169], v[134:137], v[46:49]
	v_and_b32_e32 v173, 0xffff0000, v225
	v_lshlrev_b32_e32 v224, 16, v234
	v_and_b32_e32 v225, 0xffff0000, v234
	v_mfma_f32_16x16x32_bf16 v[42:45], v[166:169], v[130:133], v[42:45]
	v_lshlrev_b32_e32 v176, 16, v235
	v_and_b32_e32 v177, 0xffff0000, v235
	s_waitcnt lgkmcnt(2)
	v_pk_mul_f32 v[170:171], v[150:151], v[170:171]
	v_mfma_f32_16x16x32_bf16 v[38:41], v[166:169], v[138:141], v[38:41]
	v_mul_f32_e64 v172, v152, v172
	v_mul_f32_e64 v173, v153, v173
	v_pk_mul_f32 v[224:225], v[150:151], v[224:225]
	v_pk_mul_f32 v[176:177], v[152:153], v[176:177]
	v_mfma_f32_16x16x32_bf16 v[34:37], v[166:169], v[142:145], v[34:37]
	s_waitcnt vmcnt(0)
	v_lshlrev_b32_e32 v166, 16, v236
	v_and_b32_e32 v167, 0xffff0000, v236
	v_lshlrev_b32_e32 v168, 16, v237
	v_mfma_f32_16x16x32_bf16 v[30:33], v[162:165], v[134:137], v[30:33]
	v_and_b32_e32 v169, 0xffff0000, v237
	v_lshlrev_b32_e32 v204, 16, v238
	v_and_b32_e32 v205, 0xffff0000, v238
	v_mfma_f32_16x16x32_bf16 v[26:29], v[162:165], v[130:133], v[26:29]
	v_lshlrev_b32_e32 v206, 16, v239
	v_and_b32_e32 v207, 0xffff0000, v239
	v_mfma_f32_16x16x32_bf16 v[22:25], v[162:165], v[138:141], v[22:25]
	v_mfma_f32_16x16x32_bf16 v[18:21], v[162:165], v[142:145], v[18:21]
	v_lshlrev_b32_e32 v162, 16, v228
	v_and_b32_e32 v163, 0xffff0000, v228
	v_lshlrev_b32_e32 v164, 16, v229
	v_and_b32_e32 v165, 0xffff0000, v229
	v_mfma_f32_16x16x32_bf16 v[14:17], v[158:161], v[134:137], v[14:17]
	v_cvt_pk_bf16_f32 v134, v202, v203
	v_cvt_pk_bf16_f32 v135, v208, v209
	v_cvt_pk_bf16_f32 v136, v170, v171
	v_mfma_f32_16x16x32_bf16 v[10:13], v[158:161], v[130:133], v[10:13]
	v_mul_f32_e64 v132, v150, v162
	v_mul_f32_e64 v133, v151, v163
	v_cvt_pk_bf16_f32 v137, v172, v173
	v_cvt_pk_bf16_f32 v132, v132, v133
	v_mfma_f32_16x16x32_bf16 v[6:9], v[158:161], v[138:141], v[6:9]
	v_cvt_pk_bf16_f32 v138, v222, v223
	v_cvt_pk_bf16_f32 v139, v174, v175
	v_cvt_pk_bf16_f32 v140, v224, v225
	v_mfma_f32_16x16x32_bf16 v[2:5], v[158:161], v[142:145], v[2:5]
	v_mul_f32_e64 v158, v154, v166
	v_mul_f32_e64 v159, v155, v167
	v_pk_mul_f32 v[160:161], v[156:157], v[168:169]
	v_pk_mul_f32 v[166:167], v[150:151], v[204:205]
	v_pk_mul_f32 v[168:169], v[152:153], v[206:207]
	v_pk_mul_f32 v[154:155], v[154:155], v[230:231]
	v_pk_mul_f32 v[156:157], v[156:157], v[226:227]
	v_pk_mul_f32 v[150:151], v[152:153], v[164:165]
	v_cvt_pk_bf16_f32 v141, v176, v177
	v_cvt_pk_bf16_f32 v142, v158, v159
	v_cvt_pk_bf16_f32 v143, v160, v161
	v_cvt_pk_bf16_f32 v144, v166, v167
	v_cvt_pk_bf16_f32 v145, v168, v169
	v_cvt_pk_bf16_f32 v130, v154, v155
	v_cvt_pk_bf16_f32 v131, v156, v157
	v_cvt_pk_bf16_f32 v133, v150, v151
	s_waitcnt lgkmcnt(0)
	v_mfma_f32_16x16x32_bf16 v[126:129], v[146:149], v[134:137], v[126:129]
	v_mfma_f32_16x16x32_bf16 v[122:125], v[146:149], v[138:141], v[122:125]
	v_mfma_f32_16x16x32_bf16 v[118:121], v[146:149], v[142:145], v[118:121]
	v_mfma_f32_16x16x32_bf16 v[110:113], v[146:149], v[130:133], v[110:113]
	ds_read_b128 v[146:149], v216 offset:8768
	s_waitcnt lgkmcnt(0)
	v_mfma_f32_16x16x32_bf16 v[114:117], v[146:149], v[134:137], v[114:117]
	v_mfma_f32_16x16x32_bf16 v[106:109], v[146:149], v[138:141], v[106:109]
	v_mfma_f32_16x16x32_bf16 v[70:73], v[146:149], v[142:145], v[70:73]
	v_mfma_f32_16x16x32_bf16 v[58:61], v[146:149], v[130:133], v[58:61]
	ds_read_b128 v[146:149], v216 offset:13120
	s_waitcnt lgkmcnt(0)
	v_mfma_f32_16x16x32_bf16 v[66:69], v[146:149], v[134:137], v[66:69]
	v_mfma_f32_16x16x32_bf16 v[62:65], v[146:149], v[138:141], v[62:65]
	v_mfma_f32_16x16x32_bf16 v[54:57], v[146:149], v[142:145], v[54:57]
	v_mfma_f32_16x16x32_bf16 v[50:53], v[146:149], v[130:133], v[50:53]
	ds_read_b128 v[146:149], v216 offset:17472
	s_waitcnt lgkmcnt(0)
	v_mfma_f32_16x16x32_bf16 v[46:49], v[146:149], v[134:137], v[46:49]
	v_mfma_f32_16x16x32_bf16 v[42:45], v[146:149], v[138:141], v[42:45]
	v_mfma_f32_16x16x32_bf16 v[38:41], v[146:149], v[142:145], v[38:41]
	v_mfma_f32_16x16x32_bf16 v[34:37], v[146:149], v[130:133], v[34:37]
	ds_read_b128 v[146:149], v216 offset:21824
	s_waitcnt lgkmcnt(0)
	v_mfma_f32_16x16x32_bf16 v[30:33], v[146:149], v[134:137], v[30:33]
	v_mfma_f32_16x16x32_bf16 v[26:29], v[146:149], v[138:141], v[26:29]
	v_mfma_f32_16x16x32_bf16 v[22:25], v[146:149], v[142:145], v[22:25]
	v_mfma_f32_16x16x32_bf16 v[18:21], v[146:149], v[130:133], v[18:21]
	ds_read_b128 v[146:149], v216 offset:26176
	s_waitcnt lgkmcnt(0)
	v_mfma_f32_16x16x32_bf16 v[14:17], v[146:149], v[134:137], v[14:17]
	v_mfma_f32_16x16x32_bf16 v[10:13], v[146:149], v[138:141], v[10:13]
	v_mfma_f32_16x16x32_bf16 v[6:9], v[146:149], v[142:145], v[6:9]
	v_mfma_f32_16x16x32_bf16 v[2:5], v[146:149], v[130:133], v[2:5]
	ds_read_b128 v[146:149], v216 offset:30528
	v_add_u32_e32 v216, 0x80, v216
	v_mfma_f32_16x16x32_bf16 v[98:101], v[218:221], v[134:137], v[98:101]
	v_mfma_f32_16x16x32_bf16 v[94:97], v[218:221], v[138:141], v[94:97]
	v_mfma_f32_16x16x32_bf16 v[82:85], v[218:221], v[142:145], v[82:85]
	v_mfma_f32_16x16x32_bf16 v[74:77], v[218:221], v[130:133], v[74:77]
	s_waitcnt lgkmcnt(0)
	v_mfma_f32_16x16x32_bf16 v[90:93], v[146:149], v[134:137], v[90:93]
	v_mfma_f32_16x16x32_bf16 v[86:89], v[146:149], v[138:141], v[86:89]
	v_mfma_f32_16x16x32_bf16 v[78:81], v[146:149], v[142:145], v[78:81]
	v_mfma_f32_16x16x32_bf16 v[102:105], v[146:149], v[130:133], v[102:105]
	s_cbranch_scc1 .LBB0_694
	s_or_b32 s0, s35, s34
	s_ashr_i32 s1, s0, 31
	s_lshl_b64 s[0:1], s[0:1], 18
	s_add_u32 s0, s22, s0
	s_addc_u32 s1, s23, s1
	v_lshlrev_b32_e32 v184, 14, v184
	v_lshl_add_u64 v[130:131], s[0:1], 0, v[184:185]
	v_mov_b32_e32 v199, v185
	v_cvt_pk_bf16_f32 v98, v98, v99
	v_cvt_pk_bf16_f32 v99, v100, v101
	v_lshl_add_u64 v[100:101], v[130:131], 0, v[198:199]
	v_cvt_pk_bf16_f32 v74, v74, v75
	v_cvt_pk_bf16_f32 v75, v76, v77
	v_add_co_u32_e32 v76, vcc, s24, v100
	v_cvt_pk_bf16_f32 v82, v82, v83
	v_cvt_pk_bf16_f32 v83, v84, v85
	v_addc_co_u32_e32 v77, vcc, 0, v101, vcc
	global_store_dwordx2 v[100:101], v[82:83], off offset:1024
	v_add_co_u32_e32 v82, vcc, s30, v100
	global_store_dwordx2 v[100:101], v[74:75], off offset:1536
	s_nop 0
	v_addc_co_u32_e32 v83, vcc, 0, v101, vcc
	v_cvt_pk_bf16_f32 v74, v126, v127
	v_cvt_pk_bf16_f32 v75, v128, v129
	v_cvt_pk_bf16_f32 v14, v14, v15
	v_cvt_pk_bf16_f32 v15, v16, v17
	v_add_co_u32_e32 v16, vcc, s31, v100
	global_store_dwordx2 v[100:101], v[74:75], off offset:2048
	v_cvt_pk_bf16_f32 v74, v122, v123
	v_cvt_pk_bf16_f32 v75, v124, v125
	v_addc_co_u32_e32 v17, vcc, 0, v101, vcc
	v_cvt_pk_bf16_f32 v2, v2, v3
	v_cvt_pk_bf16_f32 v3, v4, v5
	global_store_dwordx2 v[100:101], v[74:75], off offset:2560
	v_cvt_pk_bf16_f32 v74, v118, v119
	v_cvt_pk_bf16_f32 v75, v120, v121
	global_store_dwordx2 v[16:17], v[2:3], off offset:1536
	v_cvt_pk_bf16_f32 v2, v90, v91
	v_cvt_pk_bf16_f32 v3, v92, v93
	global_store_dwordx2 v[100:101], v[74:75], off offset:3072
	v_cvt_pk_bf16_f32 v74, v110, v111
	v_cvt_pk_bf16_f32 v75, v112, v113
	v_cvt_pk_bf16_f32 v58, v58, v59
	v_cvt_pk_bf16_f32 v59, v60, v61
	global_store_dwordx2 v[16:17], v[2:3], off offset:2048
	v_cvt_pk_bf16_f32 v2, v86, v87
	v_cvt_pk_bf16_f32 v3, v88, v89
	global_store_dwordx2 v[100:101], v[74:75], off offset:3584
	v_cvt_pk_bf16_f32 v74, v114, v115
	v_cvt_pk_bf16_f32 v75, v116, v117
	global_store_dwordx2 v[76:77], v[58:59], off offset:1536
	v_cvt_pk_bf16_f32 v58, v66, v67
	v_cvt_pk_bf16_f32 v59, v68, v69
	global_store_dwordx2 v[16:17], v[2:3], off offset:2560
	v_cvt_pk_bf16_f32 v2, v78, v79
	v_cvt_pk_bf16_f32 v3, v80, v81
	s_add_i32 s33, s33, s96
	s_xor_b64 s[14:15], s[14:15], s[16:17]
	v_cvt_pk_bf16_f32 v94, v94, v95
	v_cvt_pk_bf16_f32 v95, v96, v97
	global_store_dwordx2 v[82:83], v[74:75], off offset:-4096
	v_cvt_pk_bf16_f32 v74, v106, v107
	v_cvt_pk_bf16_f32 v75, v108, v109
	v_cvt_pk_bf16_f32 v70, v70, v71
	v_cvt_pk_bf16_f32 v71, v72, v73
	global_store_dwordx2 v[76:77], v[58:59], off offset:2048
	v_cvt_pk_bf16_f32 v58, v62, v63
	v_cvt_pk_bf16_f32 v59, v64, v65
	v_cvt_pk_bf16_f32 v54, v54, v55
	v_cvt_pk_bf16_f32 v55, v56, v57
	v_cvt_pk_bf16_f32 v50, v50, v51
	v_cvt_pk_bf16_f32 v51, v52, v53
	v_cvt_pk_bf16_f32 v46, v46, v47
	v_cvt_pk_bf16_f32 v47, v48, v49
	v_cvt_pk_bf16_f32 v42, v42, v43
	v_cvt_pk_bf16_f32 v43, v44, v45
	v_cvt_pk_bf16_f32 v38, v38, v39
	v_cvt_pk_bf16_f32 v39, v40, v41
	v_cvt_pk_bf16_f32 v34, v34, v35
	v_cvt_pk_bf16_f32 v35, v36, v37
	v_cvt_pk_bf16_f32 v30, v30, v31
	v_cvt_pk_bf16_f32 v31, v32, v33
	v_cvt_pk_bf16_f32 v26, v26, v27
	v_cvt_pk_bf16_f32 v27, v28, v29
	v_cvt_pk_bf16_f32 v22, v22, v23
	v_cvt_pk_bf16_f32 v23, v24, v25
	v_cvt_pk_bf16_f32 v18, v18, v19
	v_cvt_pk_bf16_f32 v19, v20, v21
	v_cvt_pk_bf16_f32 v10, v10, v11
	v_cvt_pk_bf16_f32 v11, v12, v13
	v_cvt_pk_bf16_f32 v6, v6, v7
	v_cvt_pk_bf16_f32 v7, v8, v9
	global_store_dwordx2 v[16:17], v[2:3], off offset:3072
	v_cvt_pk_bf16_f32 v2, v102, v103
	v_cvt_pk_bf16_f32 v3, v104, v105
	s_cmpk_lt_i32 s33, 0x100
	global_store_dwordx2 v[100:101], v[98:99], off
	global_store_dwordx2 v[100:101], v[94:95], off offset:512
	global_store_dwordx2 v[76:77], v[74:75], off offset:512
	global_store_dwordx2 v[76:77], v[70:71], off offset:1024
	global_store_dwordx2 v[76:77], v[58:59], off offset:2560
	global_store_dwordx2 v[76:77], v[54:55], off offset:3072
	global_store_dwordx2 v[76:77], v[50:51], off offset:3584
	global_store_dwordx2 v[82:83], v[46:47], off
	global_store_dwordx2 v[82:83], v[42:43], off offset:512
	global_store_dwordx2 v[82:83], v[38:39], off offset:1024
	global_store_dwordx2 v[82:83], v[34:35], off offset:1536
	global_store_dwordx2 v[82:83], v[30:31], off offset:2048
	global_store_dwordx2 v[82:83], v[26:27], off offset:2560
	global_store_dwordx2 v[82:83], v[22:23], off offset:3072
	global_store_dwordx2 v[82:83], v[18:19], off offset:3584
	global_store_dwordx2 v[16:17], v[14:15], off
	global_store_dwordx2 v[16:17], v[10:11], off offset:512
	global_store_dwordx2 v[16:17], v[6:7], off offset:1024
	global_store_dwordx2 v[16:17], v[2:3], off offset:3584
	s_barrier
	s_cbranch_scc1 .LBB0_693
